# blocks 256..383 (co-resident with the long rwkv chains) take no attention tiles and go straight to the gate-column GEMM tiles; late tile k-loop pipelined
# speedup vs baseline: 1.0201x; 1.0113x over previous
; __device__ __forceinline__ void phase_mixers(const Params& p, int l, unsigned char* smem) {
;     ...
;     for (;;) {
;       __syncthreads();
;       if (tid == 0) *tsl = (int)atomicAdd(&p.ctrs[l], 1u);
;       __syncthreads();
;       const int t = *tsl;
;       if (t >= natt) break;
.LBB0_508:
	s_barrier
	s_and_saveexec_b64 s[44:45], s[42:43]
	s_cbranch_execz .LBB0_512
	s_mov_b64 s[48:49], exec
	v_mbcnt_lo_u32_b32 v0, s48, 0
	v_mbcnt_hi_u32_b32 v0, s49, v0
	v_cmp_eq_u32_e32 vcc, 0, v0
	s_and_saveexec_b64 s[46:47], vcc
	s_cbranch_execz .LBB0_511
	s_bcnt1_i32_b64 s28, s[48:49]
	v_mov_b32_e32 v1, s28
	v_readlane_b32 s0, v255, 38
	s_nop 0
	s_sub_i32 s0, s0, 256
	s_cmp_lt_u32 s0, 128
	s_cbranch_scc1 .Latt_skip
	global_atomic_add v1, v164, v1, s[52:53] sc0
	s_branch .LBB0_511
.Latt_skip:
	v_mov_b32_e32 v1, 0x10000
